# DeltaNet task at static wave priority 3 (was 2)
# speedup vs baseline: 1.0038x; 1.0038x over previous
; __device__ __forceinline__ int otid() { int t = threadIdx.x; asm volatile("" : "+v"(t)); return t; }
; __device__ __forceinline__ void dn_task(const Params& p, int l, int task, char* smem) {
;   const int tid = otid();
;   const int dir = task & 1, hd = (task >> 1) & 3, vh = (task >> 3) & 1, b = task >> 4;
;   float* qs = (float*)smem;
;   float* ks = qs + 32 * 68;
;   float* vs = ks + 32 * 68;
;   float* al = vs + 32 * 64;
;   float* dots = al + 64;
;   float* wl = al + 128;
;   bf16_t* rawb = (bf16_t*)(wl + 5 * 192);
;   const bf16_t* P = WS_BF(p, OFF_P);
;   const float* cw = p.in[11] + (size_t)l * 5 * 768;
;   const float Aexp = __expf(p.in[12][l * 8 + dir * 4 + hd]);
;   const float dtb = p.in[13][l * 8 + dir * 4 + hd];
;   bf16_t* O = WS_BF(p, OFF_SC) + (size_t)dir * NTOK * 256;
;   const int v = vh * 32 + (tid >> 3), kq = tid & 7;
;   for (int i = tid; i < 5 * 192; i += 256) {
;     const int j = i / 192, c = i - j * 192;
;     wl[i] = cw[j * 768 + (c >> 6) * 256 + hd * 64 + (c & 63)];
;   }
.LBB0_161:
	s_mov_b64 s[30:31], s[82:83]
	s_andn2_b64 vcc, exec, s[40:41]
	s_cbranch_vccnz .LBB0_105
	s_setprio 3
	s_and_b32 s54, s60, 1
	s_lshl_b32 s56, s54, 2
	v_readlane_b32 s2, v250, 38
	s_bfe_u32 s55, s60, 0x20001
	s_or_b32 s40, s56, s2
	s_or_b32 s40, s40, s55
	s_lshl_b32 s40, s40, 2
	v_mov_b32_e32 v0, s40
	s_load_dwordx16 s[36:51], s[0:1], 0x58
	v_mov_b32_e32 v138, v172
	s_waitcnt lgkmcnt(0)
	global_load_dword v6, v0, s[38:39]
	global_load_dword v160, v0, s[40:41]
	s_movk_i32 s40, 0x3c0
	v_cmp_gt_i32_e32 vcc, s40, v138
	s_lshl_b32 s61, s55, 6
	s_and_saveexec_b64 s[40:41], vcc
	s_cbranch_execz .LBB0_179
	v_max_i32_e32 v0, 0x2c0, v138
	v_sub_u32_e32 v0, v0, v138
	s_waitcnt vmcnt(0)
	v_add_u32_e32 v2, 0xff, v0
	s_movk_i32 s42, 0xff
	v_and_b32_e32 v4, 63, v138
	v_cmp_lt_u32_e32 vcc, s42, v2
	s_mov_b64 s[44:45], 0
	s_and_saveexec_b64 s[42:43], vcc
	s_xor_b64 s[42:43], exec, s[42:43]
	s_cbranch_execnz .LBB0_173
	s_andn2_saveexec_b64 s[42:43], s[42:43]
	s_cbranch_execnz .LBB0_176
